# grid barrier: two poll loads in flight (no sleep, no final drain); P10 next-item pop issued at the tile-loop exit
# speedup vs baseline: 1.0094x; 1.0094x over previous
.Lbk0_poll:
	v_add_u32_e32 v7, 1, v1
	v_mul_lo_u32 v7, v7, v0
	v_mov_b32_e32 v6, 0x3600
	s_mov_b32 s98, 0
	global_load_dword v253, v6, s[42:43] sc1
.Lbk0_loop:
	global_load_dword v254, v6, s[42:43] sc1
	s_add_i32 s98, s98, 1
	s_waitcnt vmcnt(1)
	v_cmp_lt_u32_e32 vcc, v253, v7
	s_cbranch_vccz .Lbk0_done
	global_load_dword v253, v6, s[42:43] sc1
	s_waitcnt vmcnt(1)
	v_cmp_lt_u32_e32 vcc, v254, v7
	s_cbranch_vccz .Lbk0_done
	s_cmp_lt_u32 s98, 0x200000
	s_cbranch_scc1 .Lbk0_loop

.Lpop_pref:
	s_waitcnt vmcnt(0)
	v_mov_b32_e32 v1, v255

.LBB0_1340:
	s_mov_b64 exec, s[4:5]
	v_mov_b32_e32 v254, 1
	global_atomic_add v255, v145, v254, s[42:43] sc0
	s_mov_b64 exec, -1
	s_mov_b32 s100, 1
	s_cmp_eq_u32 s88, 0
	s_cbranch_scc1 .Lfa_exit2
	s_mul_i32 s33, s86, 0x4800
	v_add_u32_e32 v211, s33, v151
	ds_read_b128 v[232:235], v211 offset:51200
	ds_read_b128 v[202:205], v211 offset:55808
	ds_read_b128 v[206:209], v211 offset:60416
	ds_read_b128 v[244:247], v211 offset:65024
	s_waitcnt lgkmcnt(3)
	v_mfma_f32_32x32x16_bf16 v[48:63], v[232:235], v[216:219], v[48:63]
	ds_read_b128 v[232:235], v211 offset:51232
	s_waitcnt lgkmcnt(3)
	v_mfma_f32_32x32x16_bf16 v[32:47], v[202:205], v[216:219], v[32:47]
	ds_read_b128 v[202:205], v211 offset:55840
	s_waitcnt lgkmcnt(3)
	v_mfma_f32_32x32x16_bf16 v[16:31], v[206:209], v[216:219], v[16:31]
	ds_read_b128 v[206:209], v211 offset:60448
	s_waitcnt lgkmcnt(3)
	v_mfma_f32_32x32x16_bf16 v[0:15], v[244:247], v[216:219], v[0:15]
	ds_read_b128 v[244:247], v211 offset:65056
	s_waitcnt lgkmcnt(3)
	v_mfma_f32_32x32x16_bf16 v[48:63], v[232:235], v[220:223], v[48:63]
	ds_read_b128 v[232:235], v211 offset:51264
	s_waitcnt lgkmcnt(3)
	v_mfma_f32_32x32x16_bf16 v[32:47], v[202:205], v[220:223], v[32:47]
	ds_read_b128 v[202:205], v211 offset:55872
	s_waitcnt lgkmcnt(3)
	v_mfma_f32_32x32x16_bf16 v[16:31], v[206:209], v[220:223], v[16:31]
	ds_read_b128 v[206:209], v211 offset:60480
	s_waitcnt lgkmcnt(3)
	v_mfma_f32_32x32x16_bf16 v[0:15], v[244:247], v[220:223], v[0:15]
	ds_read_b128 v[244:247], v211 offset:65088
	s_waitcnt lgkmcnt(3)
	v_mfma_f32_32x32x16_bf16 v[48:63], v[232:235], v[224:227], v[48:63]
	ds_read_b128 v[232:235], v211 offset:51296
	s_waitcnt lgkmcnt(3)
	v_mfma_f32_32x32x16_bf16 v[32:47], v[202:205], v[224:227], v[32:47]
	ds_read_b128 v[202:205], v211 offset:55904
	s_waitcnt lgkmcnt(3)
	v_mfma_f32_32x32x16_bf16 v[16:31], v[206:209], v[224:227], v[16:31]
	ds_read_b128 v[206:209], v211 offset:60512
	s_waitcnt lgkmcnt(3)
	v_mfma_f32_32x32x16_bf16 v[0:15], v[244:247], v[224:227], v[0:15]
	ds_read_b128 v[244:247], v211 offset:65120
	s_waitcnt lgkmcnt(3)
	v_mfma_f32_32x32x16_bf16 v[48:63], v[232:235], v[228:231], v[48:63]
	s_waitcnt lgkmcnt(2)
	v_mfma_f32_32x32x16_bf16 v[32:47], v[202:205], v[228:231], v[32:47]
	s_waitcnt lgkmcnt(1)
	v_mfma_f32_32x32x16_bf16 v[16:31], v[206:209], v[228:231], v[16:31]
	s_waitcnt lgkmcnt(0)
	v_mfma_f32_32x32x16_bf16 v[0:15], v[244:247], v[228:231], v[0:15]
